# v26 + attention static priority raise given to waves 0-3 instead of waves 4-7 (one-time raise per unit, no per-segment flips)
# baseline (speedup 1.0000x reference)
; #define LAS __attribute__((address_space(3)))
; __device__ __forceinline__ int v_rd_base(int lane) { return ((lane & 3) << 3) | (((lane >> 2) & 3) << 6) | (((lane >> 4) & 1) << 5) | (((lane >> 5) & 1) << 8); }
; __device__ __forceinline__ void body(const bf16_t* __restrict__ Qb, const bf16_t* __restrict__ Kh, const bf16_t* __restrict__ Vh, bf16_t* __restrict__ Ob, int seq, char* lds) {
;   int tid_ = threadIdx.x; asm volatile("" : "+v"(tid_));
;   const int tid = tid_, wid = tid >> 6, lane = tid & 63, r32 = lane & 31, hi = lane >> 5;
;   constexpr int SV = 64 * 256 * 2, SK = 64 * 128 * 2;
;   char* V_lds = lds; char* K_lds = lds + 2 * SV;
;   float* ws = (float*)(lds + 2 * SV + 2 * SK) + wid * 64; float* li_l = ws; float* al_l = ws + 32;
;   float m_reg = -1e30f, l_reg = 0; f32x16 o[8] = {}; bf16x8 qr[8];
;   const bf16_t* Qw = Qb + (long)(wid * QBLK + r32) * LDQ + hi * 8;
; #pragma unroll
;   for (int d0 = 0; d0 < 8; ++d0) qr[d0] = *reinterpret_cast<const bf16x8*>(Qw + d0 * 16);
;   const int wu = __builtin_amdgcn_readfirstlane(wid);
;   int koff[2], voff[4];
; #pragma unroll
;   for (int q = 0; q < 2; ++q) { const int row = 4 * (wu * 2 + q) + (lane >> 4); koff[q] = row * LDK + ((((lane & 15) << 4) ^ ((row & 7) << 4)) >> 1); }
; #pragma unroll
;   for (int q = 0; q < 4; ++q) { const int s = 2 * (wu * 4 + q) + (lane >> 5), kk = (s >> 3) * 8 + ((lane & 31) >> 2), k = (kk & ~0xC) | ((kk & 4) << 1) | ((kk & 8) >> 1);
;     voff[q] = k * LDV + (s & 7) * 32 + (lane & 3) * 8; }
;   const int vb0 = (int)(uintptr_t)(LAS char*)V_lds + v_rd_base(lane);
;   LAS char* Vl = (LAS char*)V_lds; LAS char* Kl = (LAS char*)K_lds;
;     ...
;   const int NT = seq / KVBLK;
;   if (wu >= 4) __builtin_amdgcn_s_setprio(2);
.LBB0_613:
	s_ashr_i32 s25, s19, 3
	s_mul_i32 s6, s25, 17
	s_add_i32 s6, s6, s21
	s_bfe_u32 s7, s19, 0x20001
	s_lshl_b32 s6, s6, 2
	s_or_b32 s8, s6, s7
	s_ashr_i32 s9, s8, 31
	s_lshl_b64 s[8:9], s[8:9], 17
	s_add_u32 s6, s2, s8
	v_mov_b32_e32 v1, v220
	s_addc_u32 s9, s3, s9
	s_lshl_b32 s8, s19, 7
	s_and_b32 s8, s8, 0x80
	v_ashrrev_i32_e32 v4, 6, v1
	v_and_b32_e32 v231, 31, v1
	v_lshlrev_b32_e32 v210, 5, v4
	s_lshl_b32 s8, s8, 1
	v_or_b32_e32 v2, v210, v231
	s_add_u32 s10, s6, s8
	v_ashrrev_i32_e32 v3, 31, v2
	s_addc_u32 s11, s9, 0
	v_bfe_u32 v232, v1, 5, 1
	v_lshlrev_b64 v[2:3], 9, v[2:3]
	v_lshl_add_u64 v[2:3], s[10:11], 0, v[2:3]
	v_lshlrev_b32_e32 v212, 4, v232
	v_mov_b32_e32 v213, v0
	v_lshl_add_u64 v[2:3], v[2:3], 0, v[212:213]
	global_load_dwordx4 v[162:165], v[2:3], off
	global_load_dwordx4 v[166:169], v[2:3], off offset:32
	global_load_dwordx4 v[170:173], v[2:3], off offset:64
	global_load_dwordx4 v[174:177], v[2:3], off offset:96
	global_load_dwordx4 v[178:181], v[2:3], off offset:128
	global_load_dwordx4 v[182:185], v[2:3], off offset:160
	global_load_dwordx4 v[186:189], v[2:3], off offset:192
	global_load_dwordx4 v[190:193], v[2:3], off offset:224
	v_readfirstlane_b32 s6, v4
	s_cmp_lt_i32 s6, 4
	s_cbranch_scc0 .LBB0_615
	s_setprio 2
